# same code as v19 with the ten GEMM K-loop heads pinned at 64B+24 via p2align
# baseline (speedup 1.0000x reference)
; template <class Epi, class Sched, bool ALIGN_EPI = false, bool SP2 = false>
; __device__ __forceinline__ void gemm_phase(PG8_LAS unsigned char* lds, const Gemm g, const Sched& S, const Epi& E) {
;     ...
;         const bool has_next = S.next(ui + 1, nxt);
;         const char* nA = has_next ? (const char*)g.A + (size_t)nxt.pm * tstep : cA; const char* nB = has_next ? (const char*)g.Bt + (size_t)nxt.pn * tstep : cB;
;         for (int t = 0; t < nt; t += 2) {
;             const bool last = (t == nt - 2);
;             const char* a1 = cA + (size_t)(t + 1) * kstep;
;             const char* a2 = last ? nA : cA + (size_t)(t + 2) * kstep; const char* b2 = last ? nB : cB + (size_t)(t + 2) * kstep;
;             const char* a3 = a2 + kstep; const char* b3 = b2 + kstep;
;     ...
;         for (int a = 0; a < 2; ++a)
; #pragma unroll
;             for (int b = 0; b < 2; ++b)
; #pragma unroll
;                 for (int m = 0; m < 4; ++m)
; #pragma unroll
;                     for (int n = 0; n < 2; ++n) acc[a][b][m][n] = (f32x4){0.f, 0.f, 0.f, 0.f};
.LBB0_212:
	s_ashr_i32 s27, s26, 31
	s_lshl_b64 s[28:29], s[26:27], 19
	s_add_u32 s28, s40, s28
	s_addc_u32 s29, s41, s29
	s_and_b64 s[30:31], s[6:7], exec
	s_cselect_b32 s0, s29, s19
	s_cselect_b32 s27, s28, s18
	s_ashr_i32 s25, s24, 31
	s_lshl_b64 s[30:31], s[24:25], 19
	s_add_u32 s30, s80, s30
	s_addc_u32 s31, s81, s31
	s_and_b64 s[36:37], s[6:7], exec
	s_cselect_b32 s25, s31, s3
	s_cselect_b32 s66, s30, s2
	s_add_u32 s36, s18, 0x40080
	s_addc_u32 s37, s19, 0
	s_add_u32 s67, s2, 0x100
	v_mov_b32_e32 v0, 0
	s_addc_u32 s68, s3, 0
	s_mov_b32 s69, -2
	v_mov_b32_e32 v1, v0
	v_mov_b32_e32 v2, v0
	v_mov_b32_e32 v3, v0
	v_mov_b32_e32 v4, v0
	v_mov_b32_e32 v5, v0
	v_mov_b32_e32 v6, v0
	v_mov_b32_e32 v7, v0
	v_mov_b32_e32 v8, v0
	v_mov_b32_e32 v9, v0
	v_mov_b32_e32 v10, v0
	v_mov_b32_e32 v11, v0
	v_mov_b32_e32 v16, v0
	v_mov_b32_e32 v17, v0
	v_mov_b32_e32 v18, v0
	v_mov_b32_e32 v19, v0
	v_mov_b32_e32 v24, v0
	v_mov_b32_e32 v25, v0
	v_mov_b32_e32 v26, v0
	v_mov_b32_e32 v27, v0
	v_mov_b32_e32 v32, v0
	v_mov_b32_e32 v33, v0
	v_mov_b32_e32 v34, v0
	v_mov_b32_e32 v35, v0
	v_mov_b32_e32 v40, v0
	v_mov_b32_e32 v41, v0
	v_mov_b32_e32 v42, v0
	v_mov_b32_e32 v43, v0
	v_mov_b32_e32 v48, v0
	v_mov_b32_e32 v49, v0
	v_mov_b32_e32 v50, v0
	v_mov_b32_e32 v51, v0
	v_mov_b32_e32 v12, v0
	v_mov_b32_e32 v13, v0
	v_mov_b32_e32 v14, v0
	v_mov_b32_e32 v15, v0
	v_mov_b32_e32 v20, v0
	v_mov_b32_e32 v21, v0
	v_mov_b32_e32 v22, v0
	v_mov_b32_e32 v23, v0
	v_mov_b32_e32 v28, v0
	v_mov_b32_e32 v29, v0
	v_mov_b32_e32 v30, v0
	v_mov_b32_e32 v31, v0
	v_mov_b32_e32 v36, v0
	v_mov_b32_e32 v37, v0
	v_mov_b32_e32 v38, v0
	v_mov_b32_e32 v39, v0
	v_mov_b32_e32 v44, v0
	v_mov_b32_e32 v45, v0
	v_mov_b32_e32 v46, v0
	v_mov_b32_e32 v47, v0
	v_mov_b32_e32 v52, v0
	v_mov_b32_e32 v53, v0
	v_mov_b32_e32 v54, v0
	v_mov_b32_e32 v55, v0
	v_mov_b32_e32 v56, v0
	v_mov_b32_e32 v57, v0
	v_mov_b32_e32 v58, v0
	v_mov_b32_e32 v59, v0
	v_mov_b32_e32 v60, v0
	v_mov_b32_e32 v61, v0
	v_mov_b32_e32 v62, v0
	v_mov_b32_e32 v63, v0
	v_mov_b32_e32 v64, v0
	v_mov_b32_e32 v65, v0
	v_mov_b32_e32 v66, v0
	v_mov_b32_e32 v67, v0
	v_mov_b32_e32 v68, v0
	v_mov_b32_e32 v69, v0
	v_mov_b32_e32 v70, v0
	v_mov_b32_e32 v71, v0
	v_mov_b32_e32 v72, v0
	v_mov_b32_e32 v73, v0
	v_mov_b32_e32 v74, v0
	v_mov_b32_e32 v75, v0
	v_mov_b32_e32 v80, v0
	s_waitcnt lgkmcnt(0)
	v_mov_b32_e32 v81, v0
	v_mov_b32_e32 v82, v0
	v_mov_b32_e32 v83, v0
	v_mov_b32_e32 v88, v0
	v_mov_b32_e32 v89, v0
	v_mov_b32_e32 v90, v0
	v_mov_b32_e32 v91, v0
	v_mov_b32_e32 v96, v0
	v_mov_b32_e32 v97, v0
	v_mov_b32_e32 v98, v0
	v_mov_b32_e32 v99, v0
	v_mov_b32_e32 v104, v0
	v_mov_b32_e32 v105, v0
	v_mov_b32_e32 v106, v0
	v_mov_b32_e32 v107, v0
	v_mov_b32_e32 v112, v0
	v_mov_b32_e32 v113, v0
	v_mov_b32_e32 v114, v0
	v_mov_b32_e32 v115, v0
	v_mov_b32_e32 v76, v0
	v_mov_b32_e32 v77, v0
	v_mov_b32_e32 v78, v0
	v_mov_b32_e32 v79, v0
	v_mov_b32_e32 v84, v0
	v_mov_b32_e32 v85, v0
	v_mov_b32_e32 v86, v0
	v_mov_b32_e32 v87, v0
	v_mov_b32_e32 v92, v0
	v_mov_b32_e32 v93, v0
	v_mov_b32_e32 v94, v0
	v_mov_b32_e32 v95, v0
	v_mov_b32_e32 v100, v0
	v_mov_b32_e32 v101, v0
	v_mov_b32_e32 v102, v0
	v_mov_b32_e32 v103, v0
	v_mov_b32_e32 v108, v0
	v_mov_b32_e32 v109, v0
	v_mov_b32_e32 v110, v0
	v_mov_b32_e32 v111, v0
	v_mov_b32_e32 v116, v0
	v_mov_b32_e32 v117, v0
	v_mov_b32_e32 v118, v0
	v_mov_b32_e32 v119, v0
	v_mov_b32_e32 v120, v0
	v_mov_b32_e32 v121, v0
	v_mov_b32_e32 v122, v0
	v_mov_b32_e32 v123, v0
	v_mov_b32_e32 v124, v0
	v_mov_b32_e32 v125, v0
	v_mov_b32_e32 v126, v0
	v_mov_b32_e32 v127, v0
	.p2align	6
	s_nop 0
	s_nop 0
	s_nop 0
	s_nop 0
	s_nop 0
	s_nop 0

; template <class Epi, class Sched, bool ALIGN_EPI = false, bool SP2 = false>
; __device__ __forceinline__ void gemm_phase(PG8_LAS unsigned char* lds, const Gemm g, const Sched& S, const Epi& E) {
;     ...
;         const bool has_next = S.next(ui + 1, nxt);
;         const char* nA = has_next ? (const char*)g.A + (size_t)nxt.pm * tstep : cA; const char* nB = has_next ? (const char*)g.Bt + (size_t)nxt.pn * tstep : cB;
;         for (int t = 0; t < nt; t += 2) {
;             const bool last = (t == nt - 2);
;             const char* a1 = cA + (size_t)(t + 1) * kstep;
;             const char* a2 = last ? nA : cA + (size_t)(t + 2) * kstep; const char* b2 = last ? nB : cB + (size_t)(t + 2) * kstep;
;             const char* a3 = a2 + kstep; const char* b3 = b2 + kstep;
;     ...
;         for (int a = 0; a < 2; ++a)
; #pragma unroll
;             for (int b = 0; b < 2; ++b)
; #pragma unroll
;                 for (int m = 0; m < 4; ++m)
; #pragma unroll
;                     for (int n = 0; n < 2; ++n) acc[a][b][m][n] = (f32x4){0.f, 0.f, 0.f, 0.f};
.LBB0_240:
	s_ashr_i32 s13, s12, 31
	s_lshl_b64 s[14:15], s[12:13], 19
	s_add_u32 s14, s24, s14
	s_addc_u32 s15, s25, s15
	s_and_b64 s[16:17], s[4:5], exec
	s_cselect_b32 s13, s15, s19
	s_cselect_b32 s48, s14, s18
	s_ashr_i32 s11, s10, 31
	s_lshl_b64 s[16:17], s[10:11], 19
	s_add_u32 s16, s40, s16
	s_addc_u32 s17, s41, s17
	s_and_b64 s[22:23], s[4:5], exec
	s_cselect_b32 s11, s17, s3
	s_cselect_b32 s49, s16, s2
	s_add_u32 s22, s18, 0x40080
	s_addc_u32 s23, s19, 0
	s_add_u32 s50, s2, 0x100
	v_mov_b32_e32 v0, 0
	s_addc_u32 s51, s3, 0
	s_mov_b32 s52, -2
	v_mov_b32_e32 v1, v0
	v_mov_b32_e32 v2, v0
	v_mov_b32_e32 v3, v0
	v_mov_b32_e32 v4, v0
	v_mov_b32_e32 v5, v0
	v_mov_b32_e32 v6, v0
	v_mov_b32_e32 v7, v0
	v_mov_b32_e32 v8, v0
	v_mov_b32_e32 v9, v0
	v_mov_b32_e32 v10, v0
	v_mov_b32_e32 v11, v0
	v_mov_b32_e32 v16, v0
	v_mov_b32_e32 v17, v0
	v_mov_b32_e32 v18, v0
	v_mov_b32_e32 v19, v0
	v_mov_b32_e32 v24, v0
	v_mov_b32_e32 v25, v0
	v_mov_b32_e32 v26, v0
	v_mov_b32_e32 v27, v0
	v_mov_b32_e32 v32, v0
	v_mov_b32_e32 v33, v0
	v_mov_b32_e32 v34, v0
	v_mov_b32_e32 v35, v0
	v_mov_b32_e32 v44, v0
	v_mov_b32_e32 v45, v0
	v_mov_b32_e32 v46, v0
	v_mov_b32_e32 v47, v0
	v_mov_b32_e32 v52, v0
	v_mov_b32_e32 v53, v0
	v_mov_b32_e32 v54, v0
	v_mov_b32_e32 v55, v0
	v_mov_b32_e32 v12, v0
	v_mov_b32_e32 v13, v0
	v_mov_b32_e32 v14, v0
	v_mov_b32_e32 v15, v0
	v_mov_b32_e32 v20, v0
	v_mov_b32_e32 v21, v0
	v_mov_b32_e32 v22, v0
	v_mov_b32_e32 v23, v0
	v_mov_b32_e32 v28, v0
	v_mov_b32_e32 v29, v0
	v_mov_b32_e32 v30, v0
	v_mov_b32_e32 v31, v0
	v_mov_b32_e32 v36, v0
	v_mov_b32_e32 v37, v0
	v_mov_b32_e32 v38, v0
	v_mov_b32_e32 v39, v0
	v_mov_b32_e32 v40, v0
	v_mov_b32_e32 v41, v0
	v_mov_b32_e32 v42, v0
	v_mov_b32_e32 v43, v0
	v_mov_b32_e32 v48, v0
	v_mov_b32_e32 v49, v0
	v_mov_b32_e32 v50, v0
	v_mov_b32_e32 v51, v0
	v_mov_b32_e32 v56, v0
	v_mov_b32_e32 v57, v0
	v_mov_b32_e32 v58, v0
	v_mov_b32_e32 v59, v0
	v_mov_b32_e32 v60, v0
	v_mov_b32_e32 v61, v0
	v_mov_b32_e32 v62, v0
	v_mov_b32_e32 v63, v0
	v_mov_b32_e32 v64, v0
	v_mov_b32_e32 v65, v0
	v_mov_b32_e32 v66, v0
	v_mov_b32_e32 v67, v0
	v_mov_b32_e32 v68, v0
	v_mov_b32_e32 v69, v0
	v_mov_b32_e32 v70, v0
	v_mov_b32_e32 v71, v0
	v_mov_b32_e32 v72, v0
	v_mov_b32_e32 v73, v0
	v_mov_b32_e32 v74, v0
	v_mov_b32_e32 v75, v0
	v_mov_b32_e32 v80, v0
	s_waitcnt lgkmcnt(0)
	v_mov_b32_e32 v81, v0
	v_mov_b32_e32 v82, v0
	v_mov_b32_e32 v83, v0
	v_mov_b32_e32 v88, v0
	v_mov_b32_e32 v89, v0
	v_mov_b32_e32 v90, v0
	v_mov_b32_e32 v91, v0
	v_mov_b32_e32 v96, v0
	v_mov_b32_e32 v97, v0
	v_mov_b32_e32 v98, v0
	v_mov_b32_e32 v99, v0
	v_mov_b32_e32 v104, v0
	v_mov_b32_e32 v105, v0
	v_mov_b32_e32 v106, v0
	v_mov_b32_e32 v107, v0
	v_mov_b32_e32 v108, v0
	v_mov_b32_e32 v109, v0
	v_mov_b32_e32 v110, v0
	v_mov_b32_e32 v111, v0
	v_mov_b32_e32 v76, v0
	v_mov_b32_e32 v77, v0
	v_mov_b32_e32 v78, v0
	v_mov_b32_e32 v79, v0
	v_mov_b32_e32 v84, v0
	v_mov_b32_e32 v85, v0
	v_mov_b32_e32 v86, v0
	v_mov_b32_e32 v87, v0
	v_mov_b32_e32 v92, v0
	v_mov_b32_e32 v93, v0
	v_mov_b32_e32 v94, v0
	v_mov_b32_e32 v95, v0
	v_mov_b32_e32 v100, v0
	v_mov_b32_e32 v101, v0
	v_mov_b32_e32 v102, v0
	v_mov_b32_e32 v103, v0
	v_mov_b32_e32 v112, v0
	v_mov_b32_e32 v113, v0
	v_mov_b32_e32 v114, v0
	v_mov_b32_e32 v115, v0
	v_mov_b32_e32 v116, v0
	v_mov_b32_e32 v117, v0
	v_mov_b32_e32 v118, v0
	v_mov_b32_e32 v119, v0
	v_mov_b32_e32 v120, v0
	v_mov_b32_e32 v121, v0
	v_mov_b32_e32 v122, v0
	v_mov_b32_e32 v123, v0
	v_mov_b32_e32 v124, v0
	v_mov_b32_e32 v125, v0
	v_mov_b32_e32 v126, v0
	v_mov_b32_e32 v127, v0
	.p2align	6
	s_nop 0
	s_nop 0
	s_nop 0
	s_nop 0
	s_nop 0
	s_nop 0

; template <class Epi, class Sched, bool ALIGN_EPI = false, bool SP2 = false>
; __device__ __forceinline__ void gemm_phase(PG8_LAS unsigned char* lds, const Gemm g, const Sched& S, const Epi& E) {
;     ...
;         const bool has_next = S.next(ui + 1, nxt);
;         const char* nA = has_next ? (const char*)g.A + (size_t)nxt.pm * tstep : cA; const char* nB = has_next ? (const char*)g.Bt + (size_t)nxt.pn * tstep : cB;
;         for (int t = 0; t < nt; t += 2) {
;             const bool last = (t == nt - 2);
;             const char* a1 = cA + (size_t)(t + 1) * kstep;
;             const char* a2 = last ? nA : cA + (size_t)(t + 2) * kstep; const char* b2 = last ? nB : cB + (size_t)(t + 2) * kstep;
;             const char* a3 = a2 + kstep; const char* b3 = b2 + kstep;
;     ...
;         for (int a = 0; a < 2; ++a)
; #pragma unroll
;             for (int b = 0; b < 2; ++b)
; #pragma unroll
;                 for (int m = 0; m < 4; ++m)
; #pragma unroll
;                     for (int n = 0; n < 2; ++n) acc[a][b][m][n] = (f32x4){0.f, 0.f, 0.f, 0.f};
.LBB0_426:
	s_ashr_i32 s17, s16, 31
	s_lshl_b64 s[22:23], s[16:17], 19
	s_add_u32 s22, s58, s22
	s_addc_u32 s23, s59, s23
	s_and_b64 s[24:25], s[6:7], exec
	s_cselect_b32 s17, s23, s19
	s_cselect_b32 s27, s22, s18
	s_ashr_i32 s15, s14, 31
	s_lshl_b64 s[24:25], s[14:15], 19
	s_add_u32 s24, s30, s24
	s_addc_u32 s25, s31, s25
	s_and_b64 s[28:29], s[6:7], exec
	s_cselect_b32 s15, s25, s3
	s_cselect_b32 s53, s24, s2
	s_add_u32 s28, s18, 0x40080
	s_addc_u32 s29, s19, 0
	s_add_u32 s54, s2, 0x100
	v_mov_b32_e32 v0, 0
	s_addc_u32 s55, s3, 0
	s_mov_b32 s60, -2
	s_waitcnt lgkmcnt(0)
	v_mov_b32_e32 v1, v0
	v_mov_b32_e32 v2, v0
	v_mov_b32_e32 v3, v0
	v_mov_b32_e32 v4, v0
	v_mov_b32_e32 v5, v0
	v_mov_b32_e32 v6, v0
	v_mov_b32_e32 v7, v0
	v_mov_b32_e32 v16, v0
	v_mov_b32_e32 v17, v0
	v_mov_b32_e32 v18, v0
	v_mov_b32_e32 v19, v0
	v_mov_b32_e32 v20, v0
	v_mov_b32_e32 v21, v0
	v_mov_b32_e32 v22, v0
	v_mov_b32_e32 v23, v0
	v_mov_b32_e32 v32, v0
	v_mov_b32_e32 v33, v0
	v_mov_b32_e32 v34, v0
	v_mov_b32_e32 v35, v0
	v_mov_b32_e32 v36, v0
	v_mov_b32_e32 v37, v0
	v_mov_b32_e32 v38, v0
	v_mov_b32_e32 v39, v0
	v_mov_b32_e32 v48, v0
	v_mov_b32_e32 v49, v0
	v_mov_b32_e32 v50, v0
	v_mov_b32_e32 v51, v0
	v_mov_b32_e32 v52, v0
	v_mov_b32_e32 v53, v0
	v_mov_b32_e32 v54, v0
	v_mov_b32_e32 v55, v0
	v_mov_b32_e32 v8, v0
	v_mov_b32_e32 v9, v0
	v_mov_b32_e32 v10, v0
	v_mov_b32_e32 v11, v0
	v_mov_b32_e32 v12, v0
	v_mov_b32_e32 v13, v0
	v_mov_b32_e32 v14, v0
	v_mov_b32_e32 v15, v0
	v_mov_b32_e32 v24, v0
	v_mov_b32_e32 v25, v0
	v_mov_b32_e32 v26, v0
	v_mov_b32_e32 v27, v0
	v_mov_b32_e32 v28, v0
	v_mov_b32_e32 v29, v0
	v_mov_b32_e32 v30, v0
	v_mov_b32_e32 v31, v0
	v_mov_b32_e32 v40, v0
	v_mov_b32_e32 v41, v0
	v_mov_b32_e32 v42, v0
	v_mov_b32_e32 v43, v0
	v_mov_b32_e32 v44, v0
	v_mov_b32_e32 v45, v0
	v_mov_b32_e32 v46, v0
	v_mov_b32_e32 v47, v0
	v_mov_b32_e32 v56, v0
	v_mov_b32_e32 v57, v0
	v_mov_b32_e32 v58, v0
	v_mov_b32_e32 v59, v0
	v_mov_b32_e32 v60, v0
	v_mov_b32_e32 v61, v0
	v_mov_b32_e32 v62, v0
	v_mov_b32_e32 v63, v0
	v_mov_b32_e32 v64, v0
	v_mov_b32_e32 v65, v0
	v_mov_b32_e32 v66, v0
	v_mov_b32_e32 v67, v0
	v_mov_b32_e32 v68, v0
	v_mov_b32_e32 v69, v0
	v_mov_b32_e32 v70, v0
	v_mov_b32_e32 v71, v0
	v_mov_b32_e32 v80, v0
	s_waitcnt lgkmcnt(0)
	v_mov_b32_e32 v81, v0
	v_mov_b32_e32 v82, v0
	v_mov_b32_e32 v83, v0
	v_mov_b32_e32 v84, v0
	v_mov_b32_e32 v85, v0
	v_mov_b32_e32 v86, v0
	v_mov_b32_e32 v87, v0
	v_mov_b32_e32 v96, v0
	v_mov_b32_e32 v97, v0
	v_mov_b32_e32 v98, v0
	v_mov_b32_e32 v99, v0
	v_mov_b32_e32 v100, v0
	v_mov_b32_e32 v101, v0
	v_mov_b32_e32 v102, v0
	v_mov_b32_e32 v103, v0
	v_mov_b32_e32 v112, v0
	v_mov_b32_e32 v113, v0
	v_mov_b32_e32 v114, v0
	v_mov_b32_e32 v115, v0
	v_mov_b32_e32 v116, v0
	v_mov_b32_e32 v117, v0
	v_mov_b32_e32 v118, v0
	v_mov_b32_e32 v119, v0
	v_mov_b32_e32 v72, v0
	v_mov_b32_e32 v73, v0
	v_mov_b32_e32 v74, v0
	v_mov_b32_e32 v75, v0
	v_mov_b32_e32 v76, v0
	v_mov_b32_e32 v77, v0
	v_mov_b32_e32 v78, v0
	v_mov_b32_e32 v79, v0
	v_mov_b32_e32 v88, v0
	v_mov_b32_e32 v89, v0
	v_mov_b32_e32 v90, v0
	v_mov_b32_e32 v91, v0
	v_mov_b32_e32 v92, v0
	v_mov_b32_e32 v93, v0
	v_mov_b32_e32 v94, v0
	v_mov_b32_e32 v95, v0
	v_mov_b32_e32 v104, v0
	v_mov_b32_e32 v105, v0
	v_mov_b32_e32 v106, v0
	v_mov_b32_e32 v107, v0
	v_mov_b32_e32 v108, v0
	v_mov_b32_e32 v109, v0
	v_mov_b32_e32 v110, v0
	v_mov_b32_e32 v111, v0
	v_mov_b32_e32 v120, v0
	v_mov_b32_e32 v121, v0
	v_mov_b32_e32 v122, v0
	v_mov_b32_e32 v123, v0
	v_mov_b32_e32 v124, v0
	v_mov_b32_e32 v125, v0
	v_mov_b32_e32 v126, v0
	v_mov_b32_e32 v127, v0
	.p2align	6
	s_nop 0
	s_nop 0
	s_nop 0
	s_nop 0
	s_nop 0
	s_nop 0

; template <class Epi, class Sched, bool ALIGN_EPI = false, bool SP2 = false>
; __device__ __forceinline__ void gemm_phase(PG8_LAS unsigned char* lds, const Gemm g, const Sched& S, const Epi& E) {
;     ...
;         const bool has_next = S.next(ui + 1, nxt);
;         const char* nA = has_next ? (const char*)g.A + (size_t)nxt.pm * tstep : cA; const char* nB = has_next ? (const char*)g.Bt + (size_t)nxt.pn * tstep : cB;
;         for (int t = 0; t < nt; t += 2) {
;             const bool last = (t == nt - 2);
;             const char* a1 = cA + (size_t)(t + 1) * kstep;
;             const char* a2 = last ? nA : cA + (size_t)(t + 2) * kstep; const char* b2 = last ? nB : cB + (size_t)(t + 2) * kstep;
;             const char* a3 = a2 + kstep; const char* b3 = b2 + kstep;
;     ...
;         for (int a = 0; a < 2; ++a)
; #pragma unroll
;             for (int b = 0; b < 2; ++b)
; #pragma unroll
;                 for (int m = 0; m < 4; ++m)
; #pragma unroll
;                     for (int n = 0; n < 2; ++n) acc[a][b][m][n] = (f32x4){0.f, 0.f, 0.f, 0.f};
.LBB0_536:
	s_ashr_i32 s25, s24, 31
	s_lshl_b64 s[26:27], s[24:25], 19
	s_add_u32 s26, s40, s26
	s_addc_u32 s27, s41, s27
	s_and_b64 s[28:29], s[4:5], exec
	s_cselect_b32 s25, s27, s19
	s_cselect_b32 s63, s26, s18
	s_ashr_i32 s23, s22, 31
	s_lshl_b64 s[28:29], s[22:23], 19
	s_add_u32 s28, s37, s28
	s_addc_u32 s29, s42, s29
	s_and_b64 s[34:35], s[4:5], exec
	s_cselect_b32 s23, s29, s3
	s_cselect_b32 s65, s28, s2
	s_add_u32 s34, s18, 0x40080
	s_addc_u32 s35, s19, 0
	s_add_u32 s66, s2, 0x100
	v_mov_b32_e32 v0, 0
	s_addc_u32 s67, s3, 0
	s_mov_b32 s68, -2
	v_mov_b32_e32 v1, v0
	v_mov_b32_e32 v2, v0
	v_mov_b32_e32 v3, v0
	v_mov_b32_e32 v4, v0
	v_mov_b32_e32 v5, v0
	v_mov_b32_e32 v6, v0
	v_mov_b32_e32 v7, v0
	v_mov_b32_e32 v16, v0
	v_mov_b32_e32 v17, v0
	v_mov_b32_e32 v18, v0
	v_mov_b32_e32 v19, v0
	v_mov_b32_e32 v20, v0
	v_mov_b32_e32 v21, v0
	v_mov_b32_e32 v22, v0
	v_mov_b32_e32 v23, v0
	v_mov_b32_e32 v32, v0
	v_mov_b32_e32 v33, v0
	v_mov_b32_e32 v34, v0
	v_mov_b32_e32 v35, v0
	v_mov_b32_e32 v36, v0
	v_mov_b32_e32 v37, v0
	v_mov_b32_e32 v38, v0
	v_mov_b32_e32 v39, v0
	v_mov_b32_e32 v48, v0
	v_mov_b32_e32 v49, v0
	v_mov_b32_e32 v50, v0
	v_mov_b32_e32 v51, v0
	v_mov_b32_e32 v52, v0
	v_mov_b32_e32 v53, v0
	v_mov_b32_e32 v54, v0
	v_mov_b32_e32 v55, v0
	v_mov_b32_e32 v8, v0
	v_mov_b32_e32 v9, v0
	v_mov_b32_e32 v10, v0
	v_mov_b32_e32 v11, v0
	v_mov_b32_e32 v12, v0
	v_mov_b32_e32 v13, v0
	v_mov_b32_e32 v14, v0
	v_mov_b32_e32 v15, v0
	v_mov_b32_e32 v24, v0
	v_mov_b32_e32 v25, v0
	v_mov_b32_e32 v26, v0
	v_mov_b32_e32 v27, v0
	v_mov_b32_e32 v28, v0
	v_mov_b32_e32 v29, v0
	v_mov_b32_e32 v30, v0
	v_mov_b32_e32 v31, v0
	v_mov_b32_e32 v40, v0
	v_mov_b32_e32 v41, v0
	v_mov_b32_e32 v42, v0
	v_mov_b32_e32 v43, v0
	v_mov_b32_e32 v44, v0
	v_mov_b32_e32 v45, v0
	v_mov_b32_e32 v46, v0
	v_mov_b32_e32 v47, v0
	v_mov_b32_e32 v56, v0
	v_mov_b32_e32 v57, v0
	v_mov_b32_e32 v58, v0
	v_mov_b32_e32 v59, v0
	v_mov_b32_e32 v60, v0
	v_mov_b32_e32 v61, v0
	v_mov_b32_e32 v62, v0
	v_mov_b32_e32 v63, v0
	v_mov_b32_e32 v64, v0
	v_mov_b32_e32 v65, v0
	v_mov_b32_e32 v66, v0
	v_mov_b32_e32 v67, v0
	v_mov_b32_e32 v68, v0
	v_mov_b32_e32 v69, v0
	v_mov_b32_e32 v70, v0
	v_mov_b32_e32 v71, v0
	v_mov_b32_e32 v80, v0
	v_mov_b32_e32 v81, v0
	v_mov_b32_e32 v82, v0
	v_mov_b32_e32 v83, v0
	v_mov_b32_e32 v84, v0
	v_mov_b32_e32 v85, v0
	v_mov_b32_e32 v86, v0
	v_mov_b32_e32 v87, v0
	v_mov_b32_e32 v96, v0
	v_mov_b32_e32 v97, v0
	v_mov_b32_e32 v98, v0
	v_mov_b32_e32 v99, v0
	v_mov_b32_e32 v100, v0
	v_mov_b32_e32 v101, v0
	v_mov_b32_e32 v102, v0
	v_mov_b32_e32 v103, v0
	v_mov_b32_e32 v108, v0
	v_mov_b32_e32 v109, v0
	v_mov_b32_e32 v110, v0
	v_mov_b32_e32 v111, v0
	v_mov_b32_e32 v112, v0
	v_mov_b32_e32 v113, v0
	v_mov_b32_e32 v114, v0
	v_mov_b32_e32 v115, v0
	v_mov_b32_e32 v72, v0
	v_mov_b32_e32 v73, v0
	v_mov_b32_e32 v74, v0
	v_mov_b32_e32 v75, v0
	v_mov_b32_e32 v76, v0
	v_mov_b32_e32 v77, v0
	v_mov_b32_e32 v78, v0
	v_mov_b32_e32 v79, v0
	v_mov_b32_e32 v88, v0
	v_mov_b32_e32 v89, v0
	v_mov_b32_e32 v90, v0
	v_mov_b32_e32 v91, v0
	v_mov_b32_e32 v92, v0
	v_mov_b32_e32 v93, v0
	v_mov_b32_e32 v94, v0
	v_mov_b32_e32 v95, v0
	v_mov_b32_e32 v104, v0
	v_mov_b32_e32 v105, v0
	v_mov_b32_e32 v106, v0
	v_mov_b32_e32 v107, v0
	v_mov_b32_e32 v116, v0
	v_mov_b32_e32 v117, v0
	v_mov_b32_e32 v118, v0
	v_mov_b32_e32 v119, v0
	v_mov_b32_e32 v120, v0
	v_mov_b32_e32 v121, v0
	v_mov_b32_e32 v122, v0
	v_mov_b32_e32 v123, v0
	v_mov_b32_e32 v124, v0
	v_mov_b32_e32 v125, v0
	v_mov_b32_e32 v126, v0
	v_mov_b32_e32 v127, v0
	.p2align	6
	s_nop 0
	s_nop 0
	s_nop 0
	s_nop 0
	s_nop 0
	s_nop 0

; template <class Epi, class Sched, bool ALIGN_EPI = false, bool SP2 = false>
; __device__ __forceinline__ void gemm_phase(PG8_LAS unsigned char* lds, const Gemm g, const Sched& S, const Epi& E) {
;     ...
;         const bool has_next = S.next(ui + 1, nxt);
;         const char* nA = has_next ? (const char*)g.A + (size_t)nxt.pm * tstep : cA; const char* nB = has_next ? (const char*)g.Bt + (size_t)nxt.pn * tstep : cB;
;         for (int t = 0; t < nt; t += 2) {
;             const bool last = (t == nt - 2);
;             const char* a1 = cA + (size_t)(t + 1) * kstep;
;             const char* a2 = last ? nA : cA + (size_t)(t + 2) * kstep; const char* b2 = last ? nB : cB + (size_t)(t + 2) * kstep;
;             const char* a3 = a2 + kstep; const char* b3 = b2 + kstep;
;     ...
;         for (int a = 0; a < 2; ++a)
; #pragma unroll
;             for (int b = 0; b < 2; ++b)
; #pragma unroll
;                 for (int m = 0; m < 4; ++m)
; #pragma unroll
;                     for (int n = 0; n < 2; ++n) acc[a][b][m][n] = (f32x4){0.f, 0.f, 0.f, 0.f};
.LBB0_614:
	s_ashr_i32 s17, s16, 31
	s_lshl_b64 s[22:23], s[16:17], 21
	s_add_u32 s22, s38, s22
	s_addc_u32 s23, s39, s23
	s_and_b64 s[24:25], s[6:7], exec
	s_cselect_b32 s17, s23, s19
	s_cselect_b32 s27, s22, s18
	s_ashr_i32 s15, s14, 31
	s_lshl_b64 s[24:25], s[14:15], 21
	s_add_u32 s24, s30, s24
	s_addc_u32 s25, s31, s25
	s_and_b64 s[28:29], s[6:7], exec
	s_cselect_b32 s15, s25, s3
	s_cselect_b32 s53, s24, s2
	s_add_u32 s28, s18, 0x100080
	s_addc_u32 s29, s19, 0
	s_add_u32 s54, s2, 0x100
	v_mov_b32_e32 v0, 0
	s_addc_u32 s55, s3, 0
	s_mov_b32 s60, -2
	s_waitcnt lgkmcnt(0)
	v_mov_b32_e32 v1, v0
	v_mov_b32_e32 v2, v0
	v_mov_b32_e32 v3, v0
	v_mov_b32_e32 v4, v0
	v_mov_b32_e32 v5, v0
	v_mov_b32_e32 v6, v0
	v_mov_b32_e32 v7, v0
	v_mov_b32_e32 v16, v0
	v_mov_b32_e32 v17, v0
	v_mov_b32_e32 v18, v0
	v_mov_b32_e32 v19, v0
	v_mov_b32_e32 v20, v0
	v_mov_b32_e32 v21, v0
	v_mov_b32_e32 v22, v0
	v_mov_b32_e32 v23, v0
	v_mov_b32_e32 v32, v0
	v_mov_b32_e32 v33, v0
	v_mov_b32_e32 v34, v0
	v_mov_b32_e32 v35, v0
	v_mov_b32_e32 v36, v0
	v_mov_b32_e32 v37, v0
	v_mov_b32_e32 v38, v0
	v_mov_b32_e32 v39, v0
	v_mov_b32_e32 v48, v0
	v_mov_b32_e32 v49, v0
	v_mov_b32_e32 v50, v0
	v_mov_b32_e32 v51, v0
	v_mov_b32_e32 v52, v0
	v_mov_b32_e32 v53, v0
	v_mov_b32_e32 v54, v0
	v_mov_b32_e32 v55, v0
	v_mov_b32_e32 v8, v0
	v_mov_b32_e32 v9, v0
	v_mov_b32_e32 v10, v0
	v_mov_b32_e32 v11, v0
	v_mov_b32_e32 v12, v0
	v_mov_b32_e32 v13, v0
	v_mov_b32_e32 v14, v0
	v_mov_b32_e32 v15, v0
	v_mov_b32_e32 v24, v0
	v_mov_b32_e32 v25, v0
	v_mov_b32_e32 v26, v0
	v_mov_b32_e32 v27, v0
	v_mov_b32_e32 v28, v0
	v_mov_b32_e32 v29, v0
	v_mov_b32_e32 v30, v0
	v_mov_b32_e32 v31, v0
	v_mov_b32_e32 v40, v0
	v_mov_b32_e32 v41, v0
	v_mov_b32_e32 v42, v0
	v_mov_b32_e32 v43, v0
	v_mov_b32_e32 v44, v0
	v_mov_b32_e32 v45, v0
	v_mov_b32_e32 v46, v0
	v_mov_b32_e32 v47, v0
	v_mov_b32_e32 v56, v0
	v_mov_b32_e32 v57, v0
	v_mov_b32_e32 v58, v0
	v_mov_b32_e32 v59, v0
	v_mov_b32_e32 v60, v0
	v_mov_b32_e32 v61, v0
	v_mov_b32_e32 v62, v0
	v_mov_b32_e32 v63, v0
	v_mov_b32_e32 v64, v0
	v_mov_b32_e32 v65, v0
	v_mov_b32_e32 v66, v0
	v_mov_b32_e32 v67, v0
	v_mov_b32_e32 v68, v0
	v_mov_b32_e32 v69, v0
	v_mov_b32_e32 v70, v0
	v_mov_b32_e32 v71, v0
	v_mov_b32_e32 v80, v0
	v_mov_b32_e32 v81, v0
	v_mov_b32_e32 v82, v0
	v_mov_b32_e32 v83, v0
	v_mov_b32_e32 v84, v0
	v_mov_b32_e32 v85, v0
	v_mov_b32_e32 v86, v0
	v_mov_b32_e32 v87, v0
	v_mov_b32_e32 v96, v0
	v_mov_b32_e32 v97, v0
	v_mov_b32_e32 v98, v0
	v_mov_b32_e32 v99, v0
	v_mov_b32_e32 v100, v0
	v_mov_b32_e32 v101, v0
	v_mov_b32_e32 v102, v0
	v_mov_b32_e32 v103, v0
	v_mov_b32_e32 v112, v0
	v_mov_b32_e32 v113, v0
	v_mov_b32_e32 v114, v0
	v_mov_b32_e32 v115, v0
	v_mov_b32_e32 v116, v0
	v_mov_b32_e32 v117, v0
	v_mov_b32_e32 v118, v0
	v_mov_b32_e32 v119, v0
	v_mov_b32_e32 v72, v0
	v_mov_b32_e32 v73, v0
	v_mov_b32_e32 v74, v0
	v_mov_b32_e32 v75, v0
	v_mov_b32_e32 v76, v0
	v_mov_b32_e32 v77, v0
	v_mov_b32_e32 v78, v0
	v_mov_b32_e32 v79, v0
	v_mov_b32_e32 v88, v0
	v_mov_b32_e32 v89, v0
	v_mov_b32_e32 v90, v0
	v_mov_b32_e32 v91, v0
	v_mov_b32_e32 v92, v0
	v_mov_b32_e32 v93, v0
	v_mov_b32_e32 v94, v0
	v_mov_b32_e32 v95, v0
	v_mov_b32_e32 v104, v0
	v_mov_b32_e32 v105, v0
	v_mov_b32_e32 v106, v0
	v_mov_b32_e32 v107, v0
	v_mov_b32_e32 v108, v0
	v_mov_b32_e32 v109, v0
	v_mov_b32_e32 v110, v0
	v_mov_b32_e32 v111, v0
	v_mov_b32_e32 v120, v0
	v_mov_b32_e32 v121, v0
	v_mov_b32_e32 v122, v0
	v_mov_b32_e32 v123, v0
	v_mov_b32_e32 v124, v0
	v_mov_b32_e32 v125, v0
	v_mov_b32_e32 v126, v0
	v_mov_b32_e32 v127, v0
	.p2align	6
	s_nop 0
	s_nop 0
	s_nop 0
	s_nop 0
	s_nop 0
	s_nop 0

; template <class Epi, class Sched, bool ALIGN_EPI = false, bool SP2 = false>
; __device__ __forceinline__ void gemm_phase(PG8_LAS unsigned char* lds, const Gemm g, const Sched& S, const Epi& E) {
;     ...
;         const bool has_next = S.next(ui + 1, nxt);
;         const char* nA = has_next ? (const char*)g.A + (size_t)nxt.pm * tstep : cA; const char* nB = has_next ? (const char*)g.Bt + (size_t)nxt.pn * tstep : cB;
;         for (int t = 0; t < nt; t += 2) {
;             const bool last = (t == nt - 2);
;             const char* a1 = cA + (size_t)(t + 1) * kstep;
;             const char* a2 = last ? nA : cA + (size_t)(t + 2) * kstep; const char* b2 = last ? nB : cB + (size_t)(t + 2) * kstep;
;             const char* a3 = a2 + kstep; const char* b3 = b2 + kstep;
;     ...
;         for (int a = 0; a < 2; ++a)
; #pragma unroll
;             for (int b = 0; b < 2; ++b)
; #pragma unroll
;                 for (int m = 0; m < 4; ++m)
; #pragma unroll
;                     for (int n = 0; n < 2; ++n) acc[a][b][m][n] = (f32x4){0.f, 0.f, 0.f, 0.f};
.LBB0_726:
	s_ashr_i32 s15, s14, 31
	s_lshl_b64 s[16:17], s[14:15], 19
	s_add_u32 s16, s40, s16
	s_addc_u32 s17, s41, s17
	s_and_b64 s[22:23], s[6:7], exec
	s_cselect_b32 s15, s17, s19
	s_cselect_b32 s55, s16, s18
	s_ashr_i32 s13, s12, 31
	s_lshl_b64 s[22:23], s[12:13], 19
	s_add_u32 s22, s33, s22
	s_addc_u32 s23, s34, s23
	s_and_b64 s[28:29], s[6:7], exec
	s_cselect_b32 s13, s23, s3
	s_cselect_b32 s60, s22, s2
	s_add_u32 s28, s18, 0x40080
	s_addc_u32 s29, s19, 0
	s_add_u32 s61, s2, 0x100
	v_mov_b32_e32 v0, 0
	s_addc_u32 s62, s3, 0
	s_mov_b32 s63, -2
	v_mov_b32_e32 v1, v0
	v_mov_b32_e32 v2, v0
	v_mov_b32_e32 v3, v0
	v_mov_b32_e32 v4, v0
	v_mov_b32_e32 v5, v0
	v_mov_b32_e32 v6, v0
	v_mov_b32_e32 v7, v0
	v_mov_b32_e32 v16, v0
	v_mov_b32_e32 v17, v0
	v_mov_b32_e32 v18, v0
	v_mov_b32_e32 v19, v0
	v_mov_b32_e32 v20, v0
	v_mov_b32_e32 v21, v0
	v_mov_b32_e32 v22, v0
	v_mov_b32_e32 v23, v0
	v_mov_b32_e32 v32, v0
	v_mov_b32_e32 v33, v0
	v_mov_b32_e32 v34, v0
	v_mov_b32_e32 v35, v0
	v_mov_b32_e32 v36, v0
	v_mov_b32_e32 v37, v0
	v_mov_b32_e32 v38, v0
	v_mov_b32_e32 v39, v0
	v_mov_b32_e32 v48, v0
	v_mov_b32_e32 v49, v0
	v_mov_b32_e32 v50, v0
	v_mov_b32_e32 v51, v0
	v_mov_b32_e32 v52, v0
	v_mov_b32_e32 v53, v0
	v_mov_b32_e32 v54, v0
	v_mov_b32_e32 v55, v0
	v_mov_b32_e32 v8, v0
	v_mov_b32_e32 v9, v0
	v_mov_b32_e32 v10, v0
	v_mov_b32_e32 v11, v0
	v_mov_b32_e32 v12, v0
	v_mov_b32_e32 v13, v0
	v_mov_b32_e32 v14, v0
	v_mov_b32_e32 v15, v0
	v_mov_b32_e32 v24, v0
	v_mov_b32_e32 v25, v0
	v_mov_b32_e32 v26, v0
	v_mov_b32_e32 v27, v0
	v_mov_b32_e32 v28, v0
	v_mov_b32_e32 v29, v0
	v_mov_b32_e32 v30, v0
	v_mov_b32_e32 v31, v0
	v_mov_b32_e32 v40, v0
	v_mov_b32_e32 v41, v0
	v_mov_b32_e32 v42, v0
	v_mov_b32_e32 v43, v0
	v_mov_b32_e32 v44, v0
	v_mov_b32_e32 v45, v0
	v_mov_b32_e32 v46, v0
	v_mov_b32_e32 v47, v0
	v_mov_b32_e32 v56, v0
	v_mov_b32_e32 v57, v0
	v_mov_b32_e32 v58, v0
	v_mov_b32_e32 v59, v0
	v_mov_b32_e32 v60, v0
	v_mov_b32_e32 v61, v0
	v_mov_b32_e32 v62, v0
	v_mov_b32_e32 v63, v0
	v_mov_b32_e32 v64, v0
	v_mov_b32_e32 v65, v0
	v_mov_b32_e32 v66, v0
	v_mov_b32_e32 v67, v0
	v_mov_b32_e32 v68, v0
	v_mov_b32_e32 v69, v0
	v_mov_b32_e32 v70, v0
	v_mov_b32_e32 v71, v0
	v_mov_b32_e32 v80, v0
	v_mov_b32_e32 v81, v0
	v_mov_b32_e32 v82, v0
	v_mov_b32_e32 v83, v0
	v_mov_b32_e32 v84, v0
	v_mov_b32_e32 v85, v0
	v_mov_b32_e32 v86, v0
	v_mov_b32_e32 v87, v0
	v_mov_b32_e32 v96, v0
	v_mov_b32_e32 v97, v0
	v_mov_b32_e32 v98, v0
	v_mov_b32_e32 v99, v0
	v_mov_b32_e32 v100, v0
	v_mov_b32_e32 v101, v0
	v_mov_b32_e32 v102, v0
	v_mov_b32_e32 v103, v0
	v_mov_b32_e32 v112, v0
	v_mov_b32_e32 v113, v0
	v_mov_b32_e32 v114, v0
	v_mov_b32_e32 v115, v0
	v_mov_b32_e32 v116, v0
	v_mov_b32_e32 v117, v0
	v_mov_b32_e32 v118, v0
	v_mov_b32_e32 v119, v0
	v_mov_b32_e32 v72, v0
	v_mov_b32_e32 v73, v0
	v_mov_b32_e32 v74, v0
	v_mov_b32_e32 v75, v0
	v_mov_b32_e32 v76, v0
	v_mov_b32_e32 v77, v0
	v_mov_b32_e32 v78, v0
	v_mov_b32_e32 v79, v0
	v_mov_b32_e32 v88, v0
	v_mov_b32_e32 v89, v0
	v_mov_b32_e32 v90, v0
	v_mov_b32_e32 v91, v0
	v_mov_b32_e32 v92, v0
	v_mov_b32_e32 v93, v0
	v_mov_b32_e32 v94, v0
	v_mov_b32_e32 v95, v0
	v_mov_b32_e32 v104, v0
	v_mov_b32_e32 v105, v0
	v_mov_b32_e32 v106, v0
	v_mov_b32_e32 v107, v0
	v_mov_b32_e32 v108, v0
	v_mov_b32_e32 v109, v0
	v_mov_b32_e32 v110, v0
	v_mov_b32_e32 v111, v0
	v_mov_b32_e32 v120, v0
	v_mov_b32_e32 v121, v0
	v_mov_b32_e32 v122, v0
	v_mov_b32_e32 v123, v0
	v_mov_b32_e32 v124, v0
	v_mov_b32_e32 v125, v0
	v_mov_b32_e32 v126, v0
	v_mov_b32_e32 v127, v0
	.p2align	6
	s_nop 0
	s_nop 0
	s_nop 0
	s_nop 0
	s_nop 0
	s_nop 0

; template <class Epi, class Sched, bool ALIGN_EPI = false, bool SP2 = false>
; __device__ __forceinline__ void gemm_phase(PG8_LAS unsigned char* lds, const Gemm g, const Sched& S, const Epi& E) {
;     ...
;         const bool has_next = S.next(ui + 1, nxt);
;         const char* nA = has_next ? (const char*)g.A + (size_t)nxt.pm * tstep : cA; const char* nB = has_next ? (const char*)g.Bt + (size_t)nxt.pn * tstep : cB;
;         for (int t = 0; t < nt; t += 2) {
;             const bool last = (t == nt - 2);
;             const char* a1 = cA + (size_t)(t + 1) * kstep;
;             const char* a2 = last ? nA : cA + (size_t)(t + 2) * kstep; const char* b2 = last ? nB : cB + (size_t)(t + 2) * kstep;
;             const char* a3 = a2 + kstep; const char* b3 = b2 + kstep;
;     ...
;         for (int a = 0; a < 2; ++a)
; #pragma unroll
;             for (int b = 0; b < 2; ++b)
; #pragma unroll
;                 for (int m = 0; m < 4; ++m)
; #pragma unroll
;                     for (int n = 0; n < 2; ++n) acc[a][b][m][n] = (f32x4){0.f, 0.f, 0.f, 0.f};
.LBB0_818:
	s_ashr_i32 s13, s12, 31
	s_lshl_b64 s[14:15], s[12:13], 19
	s_add_u32 s14, s26, s14
	s_addc_u32 s15, s27, s15
	s_and_b64 s[16:17], s[4:5], exec
	s_cselect_b32 s13, s15, s19
	s_cselect_b32 s49, s14, s18
	s_ashr_i32 s11, s10, 31
	s_lshl_b64 s[16:17], s[10:11], 19
	s_add_u32 s16, s40, s16
	s_addc_u32 s17, s41, s17
	s_and_b64 s[24:25], s[4:5], exec
	s_cselect_b32 s11, s17, s3
	s_cselect_b32 s50, s16, s2
	s_add_u32 s24, s18, 0x40080
	s_addc_u32 s25, s19, 0
	s_add_u32 s51, s2, 0x100
	v_mov_b32_e32 v0, 0
	s_addc_u32 s52, s3, 0
	s_mov_b32 s53, -2
	v_mov_b32_e32 v1, v0
	v_mov_b32_e32 v2, v0
	v_mov_b32_e32 v3, v0
	v_mov_b32_e32 v4, v0
	v_mov_b32_e32 v5, v0
	v_mov_b32_e32 v6, v0
	v_mov_b32_e32 v7, v0
	v_mov_b32_e32 v8, v0
	v_mov_b32_e32 v9, v0
	v_mov_b32_e32 v10, v0
	v_mov_b32_e32 v11, v0
	v_mov_b32_e32 v16, v0
	v_mov_b32_e32 v17, v0
	v_mov_b32_e32 v18, v0
	v_mov_b32_e32 v19, v0
	v_mov_b32_e32 v24, v0
	v_mov_b32_e32 v25, v0
	v_mov_b32_e32 v26, v0
	v_mov_b32_e32 v27, v0
	v_mov_b32_e32 v32, v0
	v_mov_b32_e32 v33, v0
	v_mov_b32_e32 v34, v0
	v_mov_b32_e32 v35, v0
	v_mov_b32_e32 v44, v0
	v_mov_b32_e32 v45, v0
	v_mov_b32_e32 v46, v0
	v_mov_b32_e32 v47, v0
	v_mov_b32_e32 v52, v0
	v_mov_b32_e32 v53, v0
	v_mov_b32_e32 v54, v0
	v_mov_b32_e32 v55, v0
	v_mov_b32_e32 v12, v0
	v_mov_b32_e32 v13, v0
	v_mov_b32_e32 v14, v0
	v_mov_b32_e32 v15, v0
	v_mov_b32_e32 v20, v0
	v_mov_b32_e32 v21, v0
	v_mov_b32_e32 v22, v0
	v_mov_b32_e32 v23, v0
	v_mov_b32_e32 v28, v0
	v_mov_b32_e32 v29, v0
	v_mov_b32_e32 v30, v0
	v_mov_b32_e32 v31, v0
	v_mov_b32_e32 v36, v0
	v_mov_b32_e32 v37, v0
	v_mov_b32_e32 v38, v0
	v_mov_b32_e32 v39, v0
	v_mov_b32_e32 v40, v0
	v_mov_b32_e32 v41, v0
	v_mov_b32_e32 v42, v0
	v_mov_b32_e32 v43, v0
	v_mov_b32_e32 v48, v0
	v_mov_b32_e32 v49, v0
	v_mov_b32_e32 v50, v0
	v_mov_b32_e32 v51, v0
	v_mov_b32_e32 v56, v0
	v_mov_b32_e32 v57, v0
	v_mov_b32_e32 v58, v0
	v_mov_b32_e32 v59, v0
	v_mov_b32_e32 v60, v0
	v_mov_b32_e32 v61, v0
	v_mov_b32_e32 v62, v0
	v_mov_b32_e32 v63, v0
	v_mov_b32_e32 v64, v0
	v_mov_b32_e32 v65, v0
	v_mov_b32_e32 v66, v0
	v_mov_b32_e32 v67, v0
	v_mov_b32_e32 v68, v0
	v_mov_b32_e32 v69, v0
	v_mov_b32_e32 v70, v0
	v_mov_b32_e32 v71, v0
	v_mov_b32_e32 v72, v0
	v_mov_b32_e32 v73, v0
	v_mov_b32_e32 v74, v0
	v_mov_b32_e32 v75, v0
	v_mov_b32_e32 v80, v0
	v_mov_b32_e32 v81, v0
	v_mov_b32_e32 v82, v0
	v_mov_b32_e32 v83, v0
	v_mov_b32_e32 v88, v0
	v_mov_b32_e32 v89, v0
	v_mov_b32_e32 v90, v0
	v_mov_b32_e32 v91, v0
	v_mov_b32_e32 v96, v0
	v_mov_b32_e32 v97, v0
	v_mov_b32_e32 v98, v0
	v_mov_b32_e32 v99, v0
	v_mov_b32_e32 v104, v0
	v_mov_b32_e32 v105, v0
	v_mov_b32_e32 v106, v0
	v_mov_b32_e32 v107, v0
	v_mov_b32_e32 v108, v0
	v_mov_b32_e32 v109, v0
	v_mov_b32_e32 v110, v0
	v_mov_b32_e32 v111, v0
	v_mov_b32_e32 v76, v0
	v_mov_b32_e32 v77, v0
	v_mov_b32_e32 v78, v0
	v_mov_b32_e32 v79, v0
	v_mov_b32_e32 v84, v0
	v_mov_b32_e32 v85, v0
	v_mov_b32_e32 v86, v0
	v_mov_b32_e32 v87, v0
	v_mov_b32_e32 v92, v0
	v_mov_b32_e32 v93, v0
	v_mov_b32_e32 v94, v0
	v_mov_b32_e32 v95, v0
	v_mov_b32_e32 v100, v0
	v_mov_b32_e32 v101, v0
	v_mov_b32_e32 v102, v0
	v_mov_b32_e32 v103, v0
	v_mov_b32_e32 v112, v0
	v_mov_b32_e32 v113, v0
	v_mov_b32_e32 v114, v0
	v_mov_b32_e32 v115, v0
	v_mov_b32_e32 v116, v0
	v_mov_b32_e32 v117, v0
	v_mov_b32_e32 v118, v0
	v_mov_b32_e32 v119, v0
	v_mov_b32_e32 v120, v0
	v_mov_b32_e32 v121, v0
	v_mov_b32_e32 v122, v0
	v_mov_b32_e32 v123, v0
	v_mov_b32_e32 v124, v0
	v_mov_b32_e32 v125, v0
	v_mov_b32_e32 v126, v0
	v_mov_b32_e32 v127, v0
	.p2align	6
	s_nop 0
	s_nop 0
	s_nop 0
	s_nop 0
	s_nop 0
	s_nop 0

; template <class Epi, class Sched, bool ALIGN_EPI = false, bool SP2 = false>
; __device__ __forceinline__ void gemm_phase(PG8_LAS unsigned char* lds, const Gemm g, const Sched& S, const Epi& E) {
;     ...
;         const bool has_next = S.next(ui + 1, nxt);
;         const char* nA = has_next ? (const char*)g.A + (size_t)nxt.pm * tstep : cA; const char* nB = has_next ? (const char*)g.Bt + (size_t)nxt.pn * tstep : cB;
;         for (int t = 0; t < nt; t += 2) {
;             const bool last = (t == nt - 2);
;             const char* a1 = cA + (size_t)(t + 1) * kstep;
;             const char* a2 = last ? nA : cA + (size_t)(t + 2) * kstep; const char* b2 = last ? nB : cB + (size_t)(t + 2) * kstep;
;             const char* a3 = a2 + kstep; const char* b3 = b2 + kstep;
;     ...
;         for (int a = 0; a < 2; ++a)
; #pragma unroll
;             for (int b = 0; b < 2; ++b)
; #pragma unroll
;                 for (int m = 0; m < 4; ++m)
; #pragma unroll
;                     for (int n = 0; n < 2; ++n) acc[a][b][m][n] = (f32x4){0.f, 0.f, 0.f, 0.f};
.LBB0_1150:
	s_ashr_i32 s17, s16, 31
	s_lshl_b64 s[22:23], s[16:17], 19
	s_add_u32 s22, s58, s22
	s_addc_u32 s23, s59, s23
	s_and_b64 s[24:25], s[6:7], exec
	s_cselect_b32 s17, s23, s19
	s_cselect_b32 s27, s22, s18
	s_ashr_i32 s15, s14, 31
	s_lshl_b64 s[24:25], s[14:15], 19
	s_add_u32 s24, s30, s24
	s_addc_u32 s25, s31, s25
	s_and_b64 s[28:29], s[6:7], exec
	s_cselect_b32 s15, s25, s3
	s_cselect_b32 s53, s24, s2
	s_add_u32 s28, s18, 0x40080
	s_addc_u32 s29, s19, 0
	s_add_u32 s54, s2, 0x100
	v_mov_b32_e32 v0, 0
	s_addc_u32 s55, s3, 0
	s_mov_b32 s56, -2
	s_waitcnt lgkmcnt(0)
	v_mov_b32_e32 v1, v0
	v_mov_b32_e32 v2, v0
	v_mov_b32_e32 v3, v0
	v_mov_b32_e32 v4, v0
	v_mov_b32_e32 v5, v0
	v_mov_b32_e32 v6, v0
	v_mov_b32_e32 v7, v0
	v_mov_b32_e32 v16, v0
	v_mov_b32_e32 v17, v0
	v_mov_b32_e32 v18, v0
	v_mov_b32_e32 v19, v0
	v_mov_b32_e32 v20, v0
	v_mov_b32_e32 v21, v0
	v_mov_b32_e32 v22, v0
	v_mov_b32_e32 v23, v0
	v_mov_b32_e32 v32, v0
	v_mov_b32_e32 v33, v0
	v_mov_b32_e32 v34, v0
	v_mov_b32_e32 v35, v0
	v_mov_b32_e32 v36, v0
	v_mov_b32_e32 v37, v0
	v_mov_b32_e32 v38, v0
	v_mov_b32_e32 v39, v0
	v_mov_b32_e32 v48, v0
	v_mov_b32_e32 v49, v0
	v_mov_b32_e32 v50, v0
	v_mov_b32_e32 v51, v0
	v_mov_b32_e32 v52, v0
	v_mov_b32_e32 v53, v0
	v_mov_b32_e32 v54, v0
	v_mov_b32_e32 v55, v0
	v_mov_b32_e32 v8, v0
	v_mov_b32_e32 v9, v0
	v_mov_b32_e32 v10, v0
	v_mov_b32_e32 v11, v0
	v_mov_b32_e32 v12, v0
	v_mov_b32_e32 v13, v0
	v_mov_b32_e32 v14, v0
	v_mov_b32_e32 v15, v0
	v_mov_b32_e32 v24, v0
	v_mov_b32_e32 v25, v0
	v_mov_b32_e32 v26, v0
	v_mov_b32_e32 v27, v0
	v_mov_b32_e32 v28, v0
	v_mov_b32_e32 v29, v0
	v_mov_b32_e32 v30, v0
	v_mov_b32_e32 v31, v0
	v_mov_b32_e32 v40, v0
	v_mov_b32_e32 v41, v0
	v_mov_b32_e32 v42, v0
	v_mov_b32_e32 v43, v0
	v_mov_b32_e32 v44, v0
	v_mov_b32_e32 v45, v0
	v_mov_b32_e32 v46, v0
	v_mov_b32_e32 v47, v0
	v_mov_b32_e32 v56, v0
	v_mov_b32_e32 v57, v0
	v_mov_b32_e32 v58, v0
	v_mov_b32_e32 v59, v0
	v_mov_b32_e32 v60, v0
	v_mov_b32_e32 v61, v0
	v_mov_b32_e32 v62, v0
	v_mov_b32_e32 v63, v0
	v_mov_b32_e32 v64, v0
	v_mov_b32_e32 v65, v0
	v_mov_b32_e32 v66, v0
	v_mov_b32_e32 v67, v0
	v_mov_b32_e32 v68, v0
	v_mov_b32_e32 v69, v0
	v_mov_b32_e32 v70, v0
	v_mov_b32_e32 v71, v0
	v_mov_b32_e32 v80, v0
	v_mov_b32_e32 v81, v0
	v_mov_b32_e32 v82, v0
	v_mov_b32_e32 v83, v0
	v_mov_b32_e32 v84, v0
	v_mov_b32_e32 v85, v0
	v_mov_b32_e32 v86, v0
	v_mov_b32_e32 v87, v0
	v_mov_b32_e32 v96, v0
	v_mov_b32_e32 v97, v0
	v_mov_b32_e32 v98, v0
	v_mov_b32_e32 v99, v0
	v_mov_b32_e32 v100, v0
	v_mov_b32_e32 v101, v0
	v_mov_b32_e32 v102, v0
	v_mov_b32_e32 v103, v0
	v_mov_b32_e32 v112, v0
	v_mov_b32_e32 v113, v0
	v_mov_b32_e32 v114, v0
	v_mov_b32_e32 v115, v0
	v_mov_b32_e32 v116, v0
	v_mov_b32_e32 v117, v0
	v_mov_b32_e32 v118, v0
	v_mov_b32_e32 v119, v0
	v_mov_b32_e32 v72, v0
	v_mov_b32_e32 v73, v0
	v_mov_b32_e32 v74, v0
	v_mov_b32_e32 v75, v0
	v_mov_b32_e32 v76, v0
	v_mov_b32_e32 v77, v0
	v_mov_b32_e32 v78, v0
	v_mov_b32_e32 v79, v0
	v_mov_b32_e32 v88, v0
	v_mov_b32_e32 v89, v0
	v_mov_b32_e32 v90, v0
	v_mov_b32_e32 v91, v0
	v_mov_b32_e32 v92, v0
	v_mov_b32_e32 v93, v0
	v_mov_b32_e32 v94, v0
	v_mov_b32_e32 v95, v0
	v_mov_b32_e32 v104, v0
	v_mov_b32_e32 v105, v0
	v_mov_b32_e32 v106, v0
	v_mov_b32_e32 v107, v0
	v_mov_b32_e32 v108, v0
	v_mov_b32_e32 v109, v0
	v_mov_b32_e32 v110, v0
	v_mov_b32_e32 v111, v0
	v_mov_b32_e32 v120, v0
	v_mov_b32_e32 v121, v0
	v_mov_b32_e32 v122, v0
	v_mov_b32_e32 v123, v0
	v_mov_b32_e32 v124, v0
	v_mov_b32_e32 v125, v0
	v_mov_b32_e32 v126, v0
	v_mov_b32_e32 v127, v0
	.p2align	6
	s_nop 0
	s_nop 0
	s_nop 0
	s_nop 0
	s_nop 0
	s_nop 0

; template <class Epi, class Sched, bool ALIGN_EPI = false, bool SP2 = false>
; __device__ __forceinline__ void gemm_phase(PG8_LAS unsigned char* lds, const Gemm g, const Sched& S, const Epi& E) {
;     ...
;         const bool has_next = S.next(ui + 1, nxt);
;         const char* nA = has_next ? (const char*)g.A + (size_t)nxt.pm * tstep : cA; const char* nB = has_next ? (const char*)g.Bt + (size_t)nxt.pn * tstep : cB;
;         for (int t = 0; t < nt; t += 2) {
;             const bool last = (t == nt - 2);
;             const char* a1 = cA + (size_t)(t + 1) * kstep;
;             const char* a2 = last ? nA : cA + (size_t)(t + 2) * kstep; const char* b2 = last ? nB : cB + (size_t)(t + 2) * kstep;
;             const char* a3 = a2 + kstep; const char* b3 = b2 + kstep;
;     ...
;         for (int a = 0; a < 2; ++a)
; #pragma unroll
;             for (int b = 0; b < 2; ++b)
; #pragma unroll
;                 for (int m = 0; m < 4; ++m)
; #pragma unroll
;                     for (int n = 0; n < 2; ++n) acc[a][b][m][n] = (f32x4){0.f, 0.f, 0.f, 0.f};
.LBB0_1260:
	s_ashr_i32 s23, s22, 31
	s_lshl_b64 s[24:25], s[22:23], 19
	s_add_u32 s24, s40, s24
	s_addc_u32 s25, s41, s25
	s_and_b64 s[26:27], s[4:5], exec
	s_cselect_b32 s23, s25, s19
	s_cselect_b32 s57, s24, s18
	s_ashr_i32 s21, s20, 31
	s_lshl_b64 s[26:27], s[20:21], 19
	s_add_u32 s26, s35, s26
	s_addc_u32 s27, s36, s27
	s_and_b64 s[30:31], s[4:5], exec
	s_mov_b64 s[66:67], s[58:59]
	s_cselect_b32 s21, s27, s3
	s_cselect_b32 s58, s26, s2
	s_add_u32 s30, s18, 0x40080
	s_addc_u32 s31, s19, 0
	s_add_u32 s59, s2, 0x100
	v_mov_b32_e32 v0, 0
	s_addc_u32 s60, s3, 0
	s_mov_b32 s61, -2
	v_mov_b32_e32 v1, v0
	v_mov_b32_e32 v2, v0
	v_mov_b32_e32 v3, v0
	v_mov_b32_e32 v4, v0
	v_mov_b32_e32 v5, v0
	v_mov_b32_e32 v6, v0
	v_mov_b32_e32 v7, v0
	v_mov_b32_e32 v16, v0
	v_mov_b32_e32 v17, v0
	v_mov_b32_e32 v18, v0
	v_mov_b32_e32 v19, v0
	v_mov_b32_e32 v20, v0
	v_mov_b32_e32 v21, v0
	v_mov_b32_e32 v22, v0
	v_mov_b32_e32 v23, v0
	v_mov_b32_e32 v32, v0
	v_mov_b32_e32 v33, v0
	v_mov_b32_e32 v34, v0
	v_mov_b32_e32 v35, v0
	v_mov_b32_e32 v36, v0
	v_mov_b32_e32 v37, v0
	v_mov_b32_e32 v38, v0
	v_mov_b32_e32 v39, v0
	v_mov_b32_e32 v48, v0
	v_mov_b32_e32 v49, v0
	v_mov_b32_e32 v50, v0
	v_mov_b32_e32 v51, v0
	v_mov_b32_e32 v52, v0
	v_mov_b32_e32 v53, v0
	v_mov_b32_e32 v54, v0
	v_mov_b32_e32 v55, v0
	v_mov_b32_e32 v8, v0
	v_mov_b32_e32 v9, v0
	v_mov_b32_e32 v10, v0
	v_mov_b32_e32 v11, v0
	v_mov_b32_e32 v12, v0
	v_mov_b32_e32 v13, v0
	v_mov_b32_e32 v14, v0
	v_mov_b32_e32 v15, v0
	v_mov_b32_e32 v24, v0
	v_mov_b32_e32 v25, v0
	v_mov_b32_e32 v26, v0
	v_mov_b32_e32 v27, v0
	v_mov_b32_e32 v28, v0
	v_mov_b32_e32 v29, v0
	v_mov_b32_e32 v30, v0
	v_mov_b32_e32 v31, v0
	v_mov_b32_e32 v40, v0
	v_mov_b32_e32 v41, v0
	v_mov_b32_e32 v42, v0
	v_mov_b32_e32 v43, v0
	v_mov_b32_e32 v44, v0
	v_mov_b32_e32 v45, v0
	v_mov_b32_e32 v46, v0
	v_mov_b32_e32 v47, v0
	v_mov_b32_e32 v56, v0
	v_mov_b32_e32 v57, v0
	v_mov_b32_e32 v58, v0
	v_mov_b32_e32 v59, v0
	v_mov_b32_e32 v60, v0
	v_mov_b32_e32 v61, v0
	v_mov_b32_e32 v62, v0
	v_mov_b32_e32 v63, v0
	v_mov_b32_e32 v64, v0
	v_mov_b32_e32 v65, v0
	v_mov_b32_e32 v66, v0
	v_mov_b32_e32 v67, v0
	v_mov_b32_e32 v68, v0
	v_mov_b32_e32 v69, v0
	v_mov_b32_e32 v70, v0
	v_mov_b32_e32 v71, v0
	v_mov_b32_e32 v80, v0
	v_mov_b32_e32 v81, v0
	v_mov_b32_e32 v82, v0
	v_mov_b32_e32 v83, v0
	v_mov_b32_e32 v84, v0
	v_mov_b32_e32 v85, v0
	v_mov_b32_e32 v86, v0
	v_mov_b32_e32 v87, v0
	v_mov_b32_e32 v96, v0
	v_mov_b32_e32 v97, v0
	v_mov_b32_e32 v98, v0
	v_mov_b32_e32 v99, v0
	v_mov_b32_e32 v100, v0
	v_mov_b32_e32 v101, v0
	v_mov_b32_e32 v102, v0
	v_mov_b32_e32 v103, v0
	v_mov_b32_e32 v108, v0
	v_mov_b32_e32 v109, v0
	v_mov_b32_e32 v110, v0
	v_mov_b32_e32 v111, v0
	v_mov_b32_e32 v112, v0
	v_mov_b32_e32 v113, v0
	v_mov_b32_e32 v114, v0
	v_mov_b32_e32 v115, v0
	v_mov_b32_e32 v72, v0
	v_mov_b32_e32 v73, v0
	v_mov_b32_e32 v74, v0
	v_mov_b32_e32 v75, v0
	v_mov_b32_e32 v76, v0
	v_mov_b32_e32 v77, v0
	v_mov_b32_e32 v78, v0
	v_mov_b32_e32 v79, v0
	v_mov_b32_e32 v88, v0
	v_mov_b32_e32 v89, v0
	v_mov_b32_e32 v90, v0
	v_mov_b32_e32 v91, v0
	v_mov_b32_e32 v92, v0
	v_mov_b32_e32 v93, v0
	v_mov_b32_e32 v94, v0
	v_mov_b32_e32 v95, v0
	v_mov_b32_e32 v104, v0
	v_mov_b32_e32 v105, v0
	v_mov_b32_e32 v106, v0
	v_mov_b32_e32 v107, v0
	v_mov_b32_e32 v116, v0
	v_mov_b32_e32 v117, v0
	v_mov_b32_e32 v118, v0
	v_mov_b32_e32 v119, v0
	v_mov_b32_e32 v120, v0
	v_mov_b32_e32 v121, v0
	v_mov_b32_e32 v122, v0
	v_mov_b32_e32 v123, v0
	v_mov_b32_e32 v124, v0
	v_mov_b32_e32 v125, v0
	v_mov_b32_e32 v126, v0
	v_mov_b32_e32 v127, v0
	.p2align	6
	s_nop 0
	s_nop 0
	s_nop 0
	s_nop 0
	s_nop 0
	s_nop 0

; template <class Epi, class Sched, bool ALIGN_EPI = false, bool SP2 = false>
; __device__ __forceinline__ void gemm_phase(PG8_LAS unsigned char* lds, const Gemm g, const Sched& S, const Epi& E) {
;     ...
;         const bool has_next = S.next(ui + 1, nxt);
;         const char* nA = has_next ? (const char*)g.A + (size_t)nxt.pm * tstep : cA; const char* nB = has_next ? (const char*)g.Bt + (size_t)nxt.pn * tstep : cB;
;         for (int t = 0; t < nt; t += 2) {
;             const bool last = (t == nt - 2);
;             const char* a1 = cA + (size_t)(t + 1) * kstep;
;             const char* a2 = last ? nA : cA + (size_t)(t + 2) * kstep; const char* b2 = last ? nB : cB + (size_t)(t + 2) * kstep;
;             const char* a3 = a2 + kstep; const char* b3 = b2 + kstep;
;     ...
;         for (int a = 0; a < 2; ++a)
; #pragma unroll
;             for (int b = 0; b < 2; ++b)
; #pragma unroll
;                 for (int m = 0; m < 4; ++m)
; #pragma unroll
;                     for (int n = 0; n < 2; ++n) acc[a][b][m][n] = (f32x4){0.f, 0.f, 0.f, 0.f};
.LBB0_1339:
	s_ashr_i32 s13, s12, 31
	s_lshl_b64 s[14:15], s[12:13], 21
	s_add_u32 s14, s38, s14
	s_addc_u32 s15, s39, s15
	s_and_b64 s[16:17], s[4:5], exec
	s_cselect_b32 s13, s15, s19
	s_cselect_b32 s44, s14, s18
	s_ashr_i32 s11, s10, 31
	s_lshl_b64 s[16:17], s[10:11], 21
	s_add_u32 s16, s25, s16
	s_addc_u32 s17, s26, s17
	s_and_b64 s[22:23], s[4:5], exec
	s_cselect_b32 s11, s17, s3
	s_cselect_b32 s45, s16, s2
	s_add_u32 s22, s18, 0x100080
	s_addc_u32 s23, s19, 0
	s_add_u32 s46, s2, 0x100
	v_mov_b32_e32 v0, 0
	s_addc_u32 s47, s3, 0
	s_mov_b32 s48, -2
	v_mov_b32_e32 v1, v0
	v_mov_b32_e32 v2, v0
	v_mov_b32_e32 v3, v0
	v_mov_b32_e32 v4, v0
	v_mov_b32_e32 v5, v0
	v_mov_b32_e32 v6, v0
	v_mov_b32_e32 v7, v0
	v_mov_b32_e32 v12, v0
	v_mov_b32_e32 v13, v0
	v_mov_b32_e32 v14, v0
	v_mov_b32_e32 v15, v0
	v_mov_b32_e32 v16, v0
	v_mov_b32_e32 v17, v0
	v_mov_b32_e32 v18, v0
	v_mov_b32_e32 v19, v0
	v_mov_b32_e32 v24, v0
	v_mov_b32_e32 v25, v0
	v_mov_b32_e32 v26, v0
	v_mov_b32_e32 v27, v0
	v_mov_b32_e32 v32, v0
	v_mov_b32_e32 v33, v0
	v_mov_b32_e32 v34, v0
	v_mov_b32_e32 v35, v0
	v_mov_b32_e32 v40, v0
	v_mov_b32_e32 v41, v0
	v_mov_b32_e32 v42, v0
	v_mov_b32_e32 v43, v0
	v_mov_b32_e32 v52, v0
	v_mov_b32_e32 v53, v0
	v_mov_b32_e32 v54, v0
	v_mov_b32_e32 v55, v0
	v_mov_b32_e32 v8, v0
	v_mov_b32_e32 v9, v0
	v_mov_b32_e32 v10, v0
	v_mov_b32_e32 v11, v0
	v_mov_b32_e32 v20, v0
	v_mov_b32_e32 v21, v0
	v_mov_b32_e32 v22, v0
	v_mov_b32_e32 v23, v0
	v_mov_b32_e32 v28, v0
	v_mov_b32_e32 v29, v0
	v_mov_b32_e32 v30, v0
	v_mov_b32_e32 v31, v0
	v_mov_b32_e32 v36, v0
	v_mov_b32_e32 v37, v0
	v_mov_b32_e32 v38, v0
	v_mov_b32_e32 v39, v0
	v_mov_b32_e32 v44, v0
	v_mov_b32_e32 v45, v0
	v_mov_b32_e32 v46, v0
	v_mov_b32_e32 v47, v0
	v_mov_b32_e32 v48, v0
	v_mov_b32_e32 v49, v0
	v_mov_b32_e32 v50, v0
	v_mov_b32_e32 v51, v0
	v_mov_b32_e32 v56, v0
	v_mov_b32_e32 v57, v0
	v_mov_b32_e32 v58, v0
	v_mov_b32_e32 v59, v0
	v_mov_b32_e32 v60, v0
	v_mov_b32_e32 v61, v0
	v_mov_b32_e32 v62, v0
	v_mov_b32_e32 v63, v0
	v_mov_b32_e32 v64, v0
	v_mov_b32_e32 v65, v0
	v_mov_b32_e32 v66, v0
	v_mov_b32_e32 v67, v0
	v_mov_b32_e32 v68, v0
	v_mov_b32_e32 v69, v0
	v_mov_b32_e32 v70, v0
	v_mov_b32_e32 v71, v0
	v_mov_b32_e32 v80, v0
	v_mov_b32_e32 v81, v0
	v_mov_b32_e32 v82, v0
	v_mov_b32_e32 v83, v0
	v_mov_b32_e32 v84, v0
	v_mov_b32_e32 v85, v0
	v_mov_b32_e32 v86, v0
	v_mov_b32_e32 v87, v0
	v_mov_b32_e32 v96, v0
	v_mov_b32_e32 v97, v0
	v_mov_b32_e32 v98, v0
	v_mov_b32_e32 v99, v0
	v_mov_b32_e32 v100, v0
	v_mov_b32_e32 v101, v0
	v_mov_b32_e32 v102, v0
	v_mov_b32_e32 v103, v0
	v_mov_b32_e32 v104, v0
	v_mov_b32_e32 v105, v0
	v_mov_b32_e32 v106, v0
	v_mov_b32_e32 v107, v0
	v_mov_b32_e32 v112, v0
	v_mov_b32_e32 v113, v0
	v_mov_b32_e32 v114, v0
	v_mov_b32_e32 v115, v0
	v_mov_b32_e32 v72, v0
	v_mov_b32_e32 v73, v0
	v_mov_b32_e32 v74, v0
	v_mov_b32_e32 v75, v0
	v_mov_b32_e32 v76, v0
	v_mov_b32_e32 v77, v0
	v_mov_b32_e32 v78, v0
	v_mov_b32_e32 v79, v0
	v_mov_b32_e32 v88, v0
	v_mov_b32_e32 v89, v0
	v_mov_b32_e32 v90, v0
	v_mov_b32_e32 v91, v0
	v_mov_b32_e32 v92, v0
	v_mov_b32_e32 v93, v0
	v_mov_b32_e32 v94, v0
	v_mov_b32_e32 v95, v0
	v_mov_b32_e32 v108, v0
	v_mov_b32_e32 v109, v0
	v_mov_b32_e32 v110, v0
	v_mov_b32_e32 v111, v0
	v_mov_b32_e32 v116, v0
	v_mov_b32_e32 v117, v0
	v_mov_b32_e32 v118, v0
	v_mov_b32_e32 v119, v0
	v_mov_b32_e32 v120, v0
	v_mov_b32_e32 v121, v0
	v_mov_b32_e32 v122, v0
	v_mov_b32_e32 v123, v0
	v_mov_b32_e32 v124, v0
	v_mov_b32_e32 v125, v0
	v_mov_b32_e32 v126, v0
	v_mov_b32_e32 v127, v0
	s_waitcnt vmcnt(0)
	.p2align	6
	s_nop 0
	s_nop 0
	s_nop 0
	s_nop 0
	s_nop 0
	s_nop 0
